# final-layer W_down epilogue: f32 output stores marked nt (the result is never re-read on the GPU); on top of saddr LDS-DMA + f32 store regrouping
# speedup vs baseline: 1.0009x; 1.0009x over previous
;     __device__ __forceinline__ void operator()(const f32x4 (&acc)[2][2][4][2], const Unit& u, int wr, int wc, int fr, int fq, const PG8_LAS float*) const {
;         const int row0 = u.pm * BM + wr * 64 + fr; const int col0 = u.pn * BM + wc * 32 + 8 * fq;
; #pragma unroll
;         for (int ai = 0; ai < 2; ++ai)
; #pragma unroll
;             for (int m = 0; m < 4; ++m) { const int row = row0 + ai * HALF + m * 16; const size_t off = (size_t)row * ldc + col0; float ss = 0.f;
; #pragma unroll
;                 for (int bj = 0; bj < 2; ++bj) {
;                     const f32x4 b0 = *(const f32x4*)(base + off + bj * HALF), b1 = *(const f32x4*)(base + off + bj * HALF + 4);
;                     const f32x4 v0 = b0 + acc[ai][bj][m][0], v1 = b1 + acc[ai][bj][m][1];
;                     *(f32x4*)(out + off + bj * HALF) = v0; *(f32x4*)(out + off + bj * HALF + 4) = v1;
.LBB0_1644:
	v_lshl_add_u32 v146, s26, 8, v150
	v_lshl_or_b32 v144, s27, 8, v152
	v_ashrrev_i32_e32 v147, 31, v146
	v_ashrrev_i32_e32 v145, 31, v144
	v_lshlrev_b64 v[148:149], 12, v[146:147]
	v_lshl_add_u64 v[156:157], s[68:69], 0, v[148:149]
	v_lshlrev_b64 v[148:149], 2, v[144:145]
	v_lshl_add_u64 v[144:145], v[156:157], 0, v[148:149]
	global_load_dwordx4 v[156:159], v[144:145], off offset:16
	global_load_dwordx4 v[160:163], v[144:145], off
	s_mov_b64 s[26:27], -1
	s_waitcnt vmcnt(0)
	v_pk_add_f32 v[122:123], v[122:123], v[158:159]
	v_pk_add_f32 v[126:127], v[126:127], v[162:163]
	v_pk_add_f32 v[124:125], v[124:125], v[160:161]
	v_pk_add_f32 v[120:121], v[120:121], v[156:157]
	v_lshl_add_u64 v[228:229], v[144:145], 0, v[230:231]
	v_lshl_add_u64 v[232:233], v[144:145], 0, v[244:245]
	s_nop 1
	v_mov_b32_dpp v236, v120 row_ror:8 row_mask:0xf bank_mask:0xf
	v_mov_b32_dpp v237, v121 row_ror:8 row_mask:0xf bank_mask:0xf
	v_mov_b32_dpp v238, v122 row_ror:8 row_mask:0xf bank_mask:0xf
	v_mov_b32_dpp v239, v123 row_ror:8 row_mask:0xf bank_mask:0xf
	v_mov_b32_dpp v240, v124 row_ror:8 row_mask:0xf bank_mask:0xf
	v_mov_b32_dpp v241, v125 row_ror:8 row_mask:0xf bank_mask:0xf
	v_mov_b32_dpp v242, v126 row_ror:8 row_mask:0xf bank_mask:0xf
	v_mov_b32_dpp v243, v127 row_ror:8 row_mask:0xf bank_mask:0xf
	s_nop 0
	v_cndmask_b32_e64 v236, v236, v124, s[98:99]
	v_cndmask_b32_e64 v237, v237, v125, s[98:99]
	v_cndmask_b32_e64 v238, v238, v126, s[98:99]
	v_cndmask_b32_e64 v239, v239, v127, s[98:99]
	v_cndmask_b32_e64 v240, v120, v240, s[98:99]
	v_cndmask_b32_e64 v241, v121, v241, s[98:99]
	v_cndmask_b32_e64 v242, v122, v242, s[98:99]
	v_cndmask_b32_e64 v243, v123, v243, s[98:99]
	global_store_dwordx4 v[228:229], v[236:239], off nt
	global_store_dwordx4 v[232:233], v[240:243], off nt
	global_load_dwordx4 v[120:123], v[144:145], off offset:528
	s_nop 0
	global_load_dwordx4 v[124:127], v[144:145], off offset:512
	s_waitcnt vmcnt(1)
	v_pk_add_f32 v[112:113], v[112:113], v[120:121]
	s_waitcnt vmcnt(0)
	v_pk_add_f32 v[118:119], v[118:119], v[126:127]
	v_pk_add_f32 v[116:117], v[116:117], v[124:125]
	v_pk_add_f32 v[114:115], v[114:115], v[122:123]
	v_lshl_add_u64 v[228:229], v[144:145], 0, v[230:231]
	v_lshl_add_u64 v[232:233], v[144:145], 0, v[244:245]
	s_nop 1
	v_mov_b32_dpp v236, v112 row_ror:8 row_mask:0xf bank_mask:0xf
	v_mov_b32_dpp v237, v113 row_ror:8 row_mask:0xf bank_mask:0xf
	v_mov_b32_dpp v238, v114 row_ror:8 row_mask:0xf bank_mask:0xf
	v_mov_b32_dpp v239, v115 row_ror:8 row_mask:0xf bank_mask:0xf
	v_mov_b32_dpp v240, v116 row_ror:8 row_mask:0xf bank_mask:0xf
	v_mov_b32_dpp v241, v117 row_ror:8 row_mask:0xf bank_mask:0xf
	v_mov_b32_dpp v242, v118 row_ror:8 row_mask:0xf bank_mask:0xf
	v_mov_b32_dpp v243, v119 row_ror:8 row_mask:0xf bank_mask:0xf
	s_nop 0
	v_cndmask_b32_e64 v236, v236, v116, s[98:99]
	v_cndmask_b32_e64 v237, v237, v117, s[98:99]
	v_cndmask_b32_e64 v238, v238, v118, s[98:99]
	v_cndmask_b32_e64 v239, v239, v119, s[98:99]
	v_cndmask_b32_e64 v240, v112, v240, s[98:99]
	v_cndmask_b32_e64 v241, v113, v241, s[98:99]
	v_cndmask_b32_e64 v242, v114, v242, s[98:99]
	v_cndmask_b32_e64 v243, v115, v243, s[98:99]
	global_store_dwordx4 v[228:229], v[236:239], off offset:512 nt
	global_store_dwordx4 v[232:233], v[240:243], off offset:512 nt
	s_nop 1
	v_or_b32_e32 v112, 16, v146
	v_ashrrev_i32_e32 v113, 31, v112
	v_lshlrev_b64 v[112:113], 12, v[112:113]
	v_lshl_add_u64 v[112:113], s[68:69], 0, v[112:113]
	v_lshl_add_u64 v[120:121], v[112:113], 0, v[148:149]
	global_load_dwordx4 v[112:115], v[120:121], off offset:16
	global_load_dwordx4 v[116:119], v[120:121], off
	s_waitcnt vmcnt(1)
	v_pk_add_f32 v[106:107], v[106:107], v[114:115]
	s_waitcnt vmcnt(0)
	v_pk_add_f32 v[110:111], v[110:111], v[118:119]
	v_pk_add_f32 v[108:109], v[108:109], v[116:117]
	v_pk_add_f32 v[104:105], v[104:105], v[112:113]
	v_lshl_add_u64 v[228:229], v[120:121], 0, v[230:231]
	v_lshl_add_u64 v[232:233], v[120:121], 0, v[244:245]
	s_nop 1
	v_mov_b32_dpp v236, v104 row_ror:8 row_mask:0xf bank_mask:0xf
	v_mov_b32_dpp v237, v105 row_ror:8 row_mask:0xf bank_mask:0xf
	v_mov_b32_dpp v238, v106 row_ror:8 row_mask:0xf bank_mask:0xf
	v_mov_b32_dpp v239, v107 row_ror:8 row_mask:0xf bank_mask:0xf
	v_mov_b32_dpp v240, v108 row_ror:8 row_mask:0xf bank_mask:0xf
	v_mov_b32_dpp v241, v109 row_ror:8 row_mask:0xf bank_mask:0xf
	v_mov_b32_dpp v242, v110 row_ror:8 row_mask:0xf bank_mask:0xf
	v_mov_b32_dpp v243, v111 row_ror:8 row_mask:0xf bank_mask:0xf
	s_nop 0
	v_cndmask_b32_e64 v236, v236, v108, s[98:99]
	v_cndmask_b32_e64 v237, v237, v109, s[98:99]
	v_cndmask_b32_e64 v238, v238, v110, s[98:99]
	v_cndmask_b32_e64 v239, v239, v111, s[98:99]
	v_cndmask_b32_e64 v240, v104, v240, s[98:99]
	v_cndmask_b32_e64 v241, v105, v241, s[98:99]
	v_cndmask_b32_e64 v242, v106, v242, s[98:99]
	v_cndmask_b32_e64 v243, v107, v243, s[98:99]
	global_store_dwordx4 v[228:229], v[236:239], off nt
	global_store_dwordx4 v[232:233], v[240:243], off nt
	global_load_dwordx4 v[104:107], v[120:121], off offset:528
	s_nop 0
	global_load_dwordx4 v[108:111], v[120:121], off offset:512
	s_waitcnt vmcnt(1)
	v_pk_add_f32 v[96:97], v[96:97], v[104:105]
	s_waitcnt vmcnt(0)
;     __device__ __forceinline__ void operator()(const f32x4 (&acc)[2][2][4][2], const Unit& u, int wr, int wc, int fr, int fq, const PG8_LAS float*) const {
;         const int row0 = u.pm * BM + wr * 64 + fr; const int col0 = u.pn * BM + wc * 32 + 8 * fq;
; #pragma unroll
;         for (int ai = 0; ai < 2; ++ai)
; #pragma unroll
;             for (int m = 0; m < 4; ++m) { const int row = row0 + ai * HALF + m * 16; const size_t off = (size_t)row * ldc + col0; float ss = 0.f;
; #pragma unroll
;                 for (int bj = 0; bj < 2; ++bj) {
;                     const f32x4 b0 = *(const f32x4*)(base + off + bj * HALF), b1 = *(const f32x4*)(base + off + bj * HALF + 4);
;                     const f32x4 v0 = b0 + acc[ai][bj][m][0], v1 = b1 + acc[ai][bj][m][1];
;                     *(f32x4*)(out + off + bj * HALF) = v0; *(f32x4*)(out + off + bj * HALF + 4) = v1;
	v_pk_add_f32 v[102:103], v[102:103], v[110:111]
	v_pk_add_f32 v[100:101], v[100:101], v[108:109]
	v_pk_add_f32 v[98:99], v[98:99], v[106:107]
	v_lshl_add_u64 v[228:229], v[120:121], 0, v[230:231]
	v_lshl_add_u64 v[232:233], v[120:121], 0, v[244:245]
	s_nop 1
	v_mov_b32_dpp v236, v96 row_ror:8 row_mask:0xf bank_mask:0xf
	v_mov_b32_dpp v237, v97 row_ror:8 row_mask:0xf bank_mask:0xf
	v_mov_b32_dpp v238, v98 row_ror:8 row_mask:0xf bank_mask:0xf
	v_mov_b32_dpp v239, v99 row_ror:8 row_mask:0xf bank_mask:0xf
	v_mov_b32_dpp v240, v100 row_ror:8 row_mask:0xf bank_mask:0xf
	v_mov_b32_dpp v241, v101 row_ror:8 row_mask:0xf bank_mask:0xf
	v_mov_b32_dpp v242, v102 row_ror:8 row_mask:0xf bank_mask:0xf
	v_mov_b32_dpp v243, v103 row_ror:8 row_mask:0xf bank_mask:0xf
	s_nop 0
	v_cndmask_b32_e64 v236, v236, v100, s[98:99]
	v_cndmask_b32_e64 v237, v237, v101, s[98:99]
	v_cndmask_b32_e64 v238, v238, v102, s[98:99]
	v_cndmask_b32_e64 v239, v239, v103, s[98:99]
	v_cndmask_b32_e64 v240, v96, v240, s[98:99]
	v_cndmask_b32_e64 v241, v97, v241, s[98:99]
	v_cndmask_b32_e64 v242, v98, v242, s[98:99]
	v_cndmask_b32_e64 v243, v99, v243, s[98:99]
	global_store_dwordx4 v[228:229], v[236:239], off offset:512 nt
	global_store_dwordx4 v[232:233], v[240:243], off offset:512 nt
	s_nop 1
	v_or_b32_e32 v96, 32, v146
	v_ashrrev_i32_e32 v97, 31, v96
	v_lshlrev_b64 v[96:97], 12, v[96:97]
	v_lshl_add_u64 v[96:97], s[68:69], 0, v[96:97]
	v_lshl_add_u64 v[104:105], v[96:97], 0, v[148:149]
	global_load_dwordx4 v[96:99], v[104:105], off offset:16
	global_load_dwordx4 v[100:103], v[104:105], off
	s_waitcnt vmcnt(1)
	v_pk_add_f32 v[90:91], v[90:91], v[98:99]
	s_waitcnt vmcnt(0)
	v_pk_add_f32 v[94:95], v[94:95], v[102:103]
	v_pk_add_f32 v[92:93], v[92:93], v[100:101]
	v_pk_add_f32 v[88:89], v[88:89], v[96:97]
	v_lshl_add_u64 v[228:229], v[104:105], 0, v[230:231]
	v_lshl_add_u64 v[232:233], v[104:105], 0, v[244:245]
	s_nop 1
	v_mov_b32_dpp v236, v88 row_ror:8 row_mask:0xf bank_mask:0xf
	v_mov_b32_dpp v237, v89 row_ror:8 row_mask:0xf bank_mask:0xf
	v_mov_b32_dpp v238, v90 row_ror:8 row_mask:0xf bank_mask:0xf
	v_mov_b32_dpp v239, v91 row_ror:8 row_mask:0xf bank_mask:0xf
	v_mov_b32_dpp v240, v92 row_ror:8 row_mask:0xf bank_mask:0xf
	v_mov_b32_dpp v241, v93 row_ror:8 row_mask:0xf bank_mask:0xf
	v_mov_b32_dpp v242, v94 row_ror:8 row_mask:0xf bank_mask:0xf
	v_mov_b32_dpp v243, v95 row_ror:8 row_mask:0xf bank_mask:0xf
	s_nop 0
	v_cndmask_b32_e64 v236, v236, v92, s[98:99]
	v_cndmask_b32_e64 v237, v237, v93, s[98:99]
	v_cndmask_b32_e64 v238, v238, v94, s[98:99]
	v_cndmask_b32_e64 v239, v239, v95, s[98:99]
	v_cndmask_b32_e64 v240, v88, v240, s[98:99]
	v_cndmask_b32_e64 v241, v89, v241, s[98:99]
	v_cndmask_b32_e64 v242, v90, v242, s[98:99]
	v_cndmask_b32_e64 v243, v91, v243, s[98:99]
	global_store_dwordx4 v[228:229], v[236:239], off nt
	global_store_dwordx4 v[232:233], v[240:243], off nt
	global_load_dwordx4 v[88:91], v[104:105], off offset:528
	s_nop 0
	global_load_dwordx4 v[92:95], v[104:105], off offset:512
	s_waitcnt vmcnt(1)
	v_pk_add_f32 v[80:81], v[80:81], v[88:89]
	s_waitcnt vmcnt(0)
	v_pk_add_f32 v[86:87], v[86:87], v[94:95]
	v_pk_add_f32 v[84:85], v[84:85], v[92:93]
	v_pk_add_f32 v[82:83], v[82:83], v[90:91]
	v_lshl_add_u64 v[228:229], v[104:105], 0, v[230:231]
	v_lshl_add_u64 v[232:233], v[104:105], 0, v[244:245]
	s_nop 1
	v_mov_b32_dpp v236, v80 row_ror:8 row_mask:0xf bank_mask:0xf
	v_mov_b32_dpp v237, v81 row_ror:8 row_mask:0xf bank_mask:0xf
	v_mov_b32_dpp v238, v82 row_ror:8 row_mask:0xf bank_mask:0xf
	v_mov_b32_dpp v239, v83 row_ror:8 row_mask:0xf bank_mask:0xf
	v_mov_b32_dpp v240, v84 row_ror:8 row_mask:0xf bank_mask:0xf
	v_mov_b32_dpp v241, v85 row_ror:8 row_mask:0xf bank_mask:0xf
	v_mov_b32_dpp v242, v86 row_ror:8 row_mask:0xf bank_mask:0xf
	v_mov_b32_dpp v243, v87 row_ror:8 row_mask:0xf bank_mask:0xf
	s_nop 0
	v_cndmask_b32_e64 v236, v236, v84, s[98:99]
	v_cndmask_b32_e64 v237, v237, v85, s[98:99]
	v_cndmask_b32_e64 v238, v238, v86, s[98:99]
	v_cndmask_b32_e64 v239, v239, v87, s[98:99]
	v_cndmask_b32_e64 v240, v80, v240, s[98:99]
	v_cndmask_b32_e64 v241, v81, v241, s[98:99]
	v_cndmask_b32_e64 v242, v82, v242, s[98:99]
	v_cndmask_b32_e64 v243, v83, v243, s[98:99]
	global_store_dwordx4 v[228:229], v[236:239], off offset:512 nt
	global_store_dwordx4 v[232:233], v[240:243], off offset:512 nt
	s_nop 1
	v_or_b32_e32 v80, 48, v146
	v_ashrrev_i32_e32 v81, 31, v80
	v_lshlrev_b64 v[80:81], 12, v[80:81]
	v_lshl_add_u64 v[80:81], s[68:69], 0, v[80:81]
	v_lshl_add_u64 v[88:89], v[80:81], 0, v[148:149]
	global_load_dwordx4 v[80:83], v[88:89], off offset:16
	global_load_dwordx4 v[84:87], v[88:89], off
	s_waitcnt vmcnt(1)
	v_pk_add_f32 v[74:75], v[74:75], v[82:83]
	s_waitcnt vmcnt(0)
	v_pk_add_f32 v[78:79], v[78:79], v[86:87]
	v_pk_add_f32 v[76:77], v[76:77], v[84:85]
	v_pk_add_f32 v[72:73], v[72:73], v[80:81]
	v_lshl_add_u64 v[228:229], v[88:89], 0, v[230:231]
	v_lshl_add_u64 v[232:233], v[88:89], 0, v[244:245]
	s_nop 1
	v_mov_b32_dpp v236, v72 row_ror:8 row_mask:0xf bank_mask:0xf
	v_mov_b32_dpp v237, v73 row_ror:8 row_mask:0xf bank_mask:0xf
	v_mov_b32_dpp v238, v74 row_ror:8 row_mask:0xf bank_mask:0xf
	v_mov_b32_dpp v239, v75 row_ror:8 row_mask:0xf bank_mask:0xf
	v_mov_b32_dpp v240, v76 row_ror:8 row_mask:0xf bank_mask:0xf
	v_mov_b32_dpp v241, v77 row_ror:8 row_mask:0xf bank_mask:0xf
	v_mov_b32_dpp v242, v78 row_ror:8 row_mask:0xf bank_mask:0xf
	v_mov_b32_dpp v243, v79 row_ror:8 row_mask:0xf bank_mask:0xf
	s_nop 0
	v_cndmask_b32_e64 v236, v236, v76, s[98:99]
	v_cndmask_b32_e64 v237, v237, v77, s[98:99]
	v_cndmask_b32_e64 v238, v238, v78, s[98:99]
	v_cndmask_b32_e64 v239, v239, v79, s[98:99]
	v_cndmask_b32_e64 v240, v72, v240, s[98:99]
	v_cndmask_b32_e64 v241, v73, v241, s[98:99]
	v_cndmask_b32_e64 v242, v74, v242, s[98:99]
	v_cndmask_b32_e64 v243, v75, v243, s[98:99]
	global_store_dwordx4 v[228:229], v[236:239], off nt
	global_store_dwordx4 v[232:233], v[240:243], off nt
	global_load_dwordx4 v[72:75], v[88:89], off offset:528
	s_nop 0
	global_load_dwordx4 v[76:79], v[88:89], off offset:512
	s_waitcnt vmcnt(1)
;     __device__ __forceinline__ void operator()(const f32x4 (&acc)[2][2][4][2], const Unit& u, int wr, int wc, int fr, int fq, const PG8_LAS float*) const {
;         const int row0 = u.pm * BM + wr * 64 + fr; const int col0 = u.pn * BM + wc * 32 + 8 * fq;
; #pragma unroll
;         for (int ai = 0; ai < 2; ++ai)
; #pragma unroll
;             for (int m = 0; m < 4; ++m) { const int row = row0 + ai * HALF + m * 16; const size_t off = (size_t)row * ldc + col0; float ss = 0.f;
; #pragma unroll
;                 for (int bj = 0; bj < 2; ++bj) {
;                     const f32x4 b0 = *(const f32x4*)(base + off + bj * HALF), b1 = *(const f32x4*)(base + off + bj * HALF + 4);
;                     const f32x4 v0 = b0 + acc[ai][bj][m][0], v1 = b1 + acc[ai][bj][m][1];
;                     *(f32x4*)(out + off + bj * HALF) = v0; *(f32x4*)(out + off + bj * HALF + 4) = v1;
	v_pk_add_f32 v[66:67], v[66:67], v[74:75]
	s_waitcnt vmcnt(0)
	v_pk_add_f32 v[70:71], v[70:71], v[78:79]
	v_pk_add_f32 v[68:69], v[68:69], v[76:77]
	v_add_co_u32_e32 v74, vcc, s50, v144
	v_pk_add_f32 v[64:65], v[64:65], v[72:73]
	v_lshl_add_u64 v[228:229], v[88:89], 0, v[230:231]
	v_lshl_add_u64 v[232:233], v[88:89], 0, v[244:245]
	s_nop 1
	v_mov_b32_dpp v236, v64 row_ror:8 row_mask:0xf bank_mask:0xf
	v_mov_b32_dpp v237, v65 row_ror:8 row_mask:0xf bank_mask:0xf
	v_mov_b32_dpp v238, v66 row_ror:8 row_mask:0xf bank_mask:0xf
	v_mov_b32_dpp v239, v67 row_ror:8 row_mask:0xf bank_mask:0xf
	v_mov_b32_dpp v240, v68 row_ror:8 row_mask:0xf bank_mask:0xf
	v_mov_b32_dpp v241, v69 row_ror:8 row_mask:0xf bank_mask:0xf
	v_mov_b32_dpp v242, v70 row_ror:8 row_mask:0xf bank_mask:0xf
	v_mov_b32_dpp v243, v71 row_ror:8 row_mask:0xf bank_mask:0xf
	s_nop 0
	v_cndmask_b32_e64 v236, v236, v68, s[98:99]
	v_cndmask_b32_e64 v237, v237, v69, s[98:99]
	v_cndmask_b32_e64 v238, v238, v70, s[98:99]
	v_cndmask_b32_e64 v239, v239, v71, s[98:99]
	v_cndmask_b32_e64 v240, v64, v240, s[98:99]
	v_cndmask_b32_e64 v241, v65, v241, s[98:99]
	v_cndmask_b32_e64 v242, v66, v242, s[98:99]
	v_cndmask_b32_e64 v243, v67, v243, s[98:99]
	global_store_dwordx4 v[228:229], v[236:239], off offset:512 nt
	global_store_dwordx4 v[232:233], v[240:243], off offset:512 nt
	v_addc_co_u32_e32 v75, vcc, 0, v145, vcc
	v_lshl_add_u64 v[72:73], v[144:145], 0, s[10:11]
	global_load_dwordx4 v[64:67], v[74:75], off
	global_load_dwordx4 v[68:71], v[72:73], off offset:16
	s_waitcnt vmcnt(1)
	v_pk_add_f32 v[62:63], v[62:63], v[66:67]
	v_pk_add_f32 v[60:61], v[60:61], v[64:65]
	s_waitcnt vmcnt(0)
	v_pk_add_f32 v[58:59], v[58:59], v[70:71]
	v_pk_add_f32 v[56:57], v[56:57], v[68:69]
	v_lshl_add_u64 v[228:229], v[74:75], 0, v[230:231]
	v_lshl_add_u64 v[232:233], v[72:73], 0, v[244:245]
	s_nop 1
	v_mov_b32_dpp v236, v56 row_ror:8 row_mask:0xf bank_mask:0xf
	v_mov_b32_dpp v237, v57 row_ror:8 row_mask:0xf bank_mask:0xf
	v_mov_b32_dpp v238, v58 row_ror:8 row_mask:0xf bank_mask:0xf
	v_mov_b32_dpp v239, v59 row_ror:8 row_mask:0xf bank_mask:0xf
	v_mov_b32_dpp v240, v60 row_ror:8 row_mask:0xf bank_mask:0xf
	v_mov_b32_dpp v241, v61 row_ror:8 row_mask:0xf bank_mask:0xf
	v_mov_b32_dpp v242, v62 row_ror:8 row_mask:0xf bank_mask:0xf
	v_mov_b32_dpp v243, v63 row_ror:8 row_mask:0xf bank_mask:0xf
	s_nop 0
	v_cndmask_b32_e64 v236, v236, v60, s[98:99]
	v_cndmask_b32_e64 v237, v237, v61, s[98:99]
	v_cndmask_b32_e64 v238, v238, v62, s[98:99]
	v_cndmask_b32_e64 v239, v239, v63, s[98:99]
	v_cndmask_b32_e64 v240, v56, v240, s[98:99]
	v_cndmask_b32_e64 v241, v57, v241, s[98:99]
	v_cndmask_b32_e64 v242, v58, v242, s[98:99]
	v_cndmask_b32_e64 v243, v59, v243, s[98:99]
	global_store_dwordx4 v[228:229], v[236:239], off nt
	global_store_dwordx4 v[232:233], v[240:243], off nt
	global_load_dwordx4 v[56:59], v[72:73], off offset:528
	s_nop 0
	global_load_dwordx4 v[60:63], v[72:73], off offset:512
	s_waitcnt vmcnt(1)
	v_pk_add_f32 v[50:51], v[50:51], v[58:59]
	s_waitcnt vmcnt(0)
	v_pk_add_f32 v[54:55], v[54:55], v[62:63]
	v_pk_add_f32 v[52:53], v[52:53], v[60:61]
	v_add_co_u32_e32 v58, vcc, s51, v144
	v_pk_add_f32 v[48:49], v[48:49], v[56:57]
	v_lshl_add_u64 v[228:229], v[72:73], 0, v[230:231]
	v_lshl_add_u64 v[232:233], v[72:73], 0, v[244:245]
	s_nop 1
	v_mov_b32_dpp v236, v48 row_ror:8 row_mask:0xf bank_mask:0xf
	v_mov_b32_dpp v237, v49 row_ror:8 row_mask:0xf bank_mask:0xf
	v_mov_b32_dpp v238, v50 row_ror:8 row_mask:0xf bank_mask:0xf
	v_mov_b32_dpp v239, v51 row_ror:8 row_mask:0xf bank_mask:0xf
	v_mov_b32_dpp v240, v52 row_ror:8 row_mask:0xf bank_mask:0xf
	v_mov_b32_dpp v241, v53 row_ror:8 row_mask:0xf bank_mask:0xf
	v_mov_b32_dpp v242, v54 row_ror:8 row_mask:0xf bank_mask:0xf
	v_mov_b32_dpp v243, v55 row_ror:8 row_mask:0xf bank_mask:0xf
	s_nop 0
	v_cndmask_b32_e64 v236, v236, v52, s[98:99]
	v_cndmask_b32_e64 v237, v237, v53, s[98:99]
	v_cndmask_b32_e64 v238, v238, v54, s[98:99]
	v_cndmask_b32_e64 v239, v239, v55, s[98:99]
	v_cndmask_b32_e64 v240, v48, v240, s[98:99]
	v_cndmask_b32_e64 v241, v49, v241, s[98:99]
	v_cndmask_b32_e64 v242, v50, v242, s[98:99]
	v_cndmask_b32_e64 v243, v51, v243, s[98:99]
	global_store_dwordx4 v[228:229], v[236:239], off offset:512 nt
	global_store_dwordx4 v[232:233], v[240:243], off offset:512 nt
	v_addc_co_u32_e32 v59, vcc, 0, v145, vcc
	v_lshl_add_u64 v[56:57], v[144:145], 0, s[12:13]
	global_load_dwordx4 v[48:51], v[58:59], off
	global_load_dwordx4 v[52:55], v[56:57], off offset:16
	s_waitcnt vmcnt(1)
	v_pk_add_f32 v[46:47], v[46:47], v[50:51]
	v_pk_add_f32 v[44:45], v[44:45], v[48:49]
	s_waitcnt vmcnt(0)
	v_pk_add_f32 v[42:43], v[42:43], v[54:55]
	v_pk_add_f32 v[40:41], v[40:41], v[52:53]
	v_lshl_add_u64 v[228:229], v[58:59], 0, v[230:231]
	v_lshl_add_u64 v[232:233], v[56:57], 0, v[244:245]
	s_nop 1
	v_mov_b32_dpp v236, v40 row_ror:8 row_mask:0xf bank_mask:0xf
	v_mov_b32_dpp v237, v41 row_ror:8 row_mask:0xf bank_mask:0xf
	v_mov_b32_dpp v238, v42 row_ror:8 row_mask:0xf bank_mask:0xf
	v_mov_b32_dpp v239, v43 row_ror:8 row_mask:0xf bank_mask:0xf
	v_mov_b32_dpp v240, v44 row_ror:8 row_mask:0xf bank_mask:0xf
	v_mov_b32_dpp v241, v45 row_ror:8 row_mask:0xf bank_mask:0xf
	v_mov_b32_dpp v242, v46 row_ror:8 row_mask:0xf bank_mask:0xf
	v_mov_b32_dpp v243, v47 row_ror:8 row_mask:0xf bank_mask:0xf
	s_nop 0
	v_cndmask_b32_e64 v236, v236, v44, s[98:99]
	v_cndmask_b32_e64 v237, v237, v45, s[98:99]
	v_cndmask_b32_e64 v238, v238, v46, s[98:99]
	v_cndmask_b32_e64 v239, v239, v47, s[98:99]
	v_cndmask_b32_e64 v240, v40, v240, s[98:99]
	v_cndmask_b32_e64 v241, v41, v241, s[98:99]
	v_cndmask_b32_e64 v242, v42, v242, s[98:99]
	v_cndmask_b32_e64 v243, v43, v243, s[98:99]
	global_store_dwordx4 v[228:229], v[236:239], off nt
	global_store_dwordx4 v[232:233], v[240:243], off nt
	global_load_dwordx4 v[40:43], v[56:57], off offset:528
	s_nop 0
	global_load_dwordx4 v[44:47], v[56:57], off offset:512
	s_waitcnt vmcnt(1)
;     __device__ __forceinline__ void operator()(const f32x4 (&acc)[2][2][4][2], const Unit& u, int wr, int wc, int fr, int fq, const PG8_LAS float*) const {
;         const int row0 = u.pm * BM + wr * 64 + fr; const int col0 = u.pn * BM + wc * 32 + 8 * fq;
; #pragma unroll
;         for (int ai = 0; ai < 2; ++ai)
; #pragma unroll
;             for (int m = 0; m < 4; ++m) { const int row = row0 + ai * HALF + m * 16; const size_t off = (size_t)row * ldc + col0; float ss = 0.f;
; #pragma unroll
;                 for (int bj = 0; bj < 2; ++bj) {
;                     const f32x4 b0 = *(const f32x4*)(base + off + bj * HALF), b1 = *(const f32x4*)(base + off + bj * HALF + 4);
;                     const f32x4 v0 = b0 + acc[ai][bj][m][0], v1 = b1 + acc[ai][bj][m][1];
;                     *(f32x4*)(out + off + bj * HALF) = v0; *(f32x4*)(out + off + bj * HALF + 4) = v1;
	v_pk_add_f32 v[34:35], v[34:35], v[42:43]
	s_waitcnt vmcnt(0)
	v_pk_add_f32 v[38:39], v[38:39], v[46:47]
	v_pk_add_f32 v[36:37], v[36:37], v[44:45]
	v_add_co_u32_e32 v42, vcc, s52, v144
	v_pk_add_f32 v[32:33], v[32:33], v[40:41]
	v_lshl_add_u64 v[228:229], v[56:57], 0, v[230:231]
	v_lshl_add_u64 v[232:233], v[56:57], 0, v[244:245]
	s_nop 1
	v_mov_b32_dpp v236, v32 row_ror:8 row_mask:0xf bank_mask:0xf
	v_mov_b32_dpp v237, v33 row_ror:8 row_mask:0xf bank_mask:0xf
	v_mov_b32_dpp v238, v34 row_ror:8 row_mask:0xf bank_mask:0xf
	v_mov_b32_dpp v239, v35 row_ror:8 row_mask:0xf bank_mask:0xf
	v_mov_b32_dpp v240, v36 row_ror:8 row_mask:0xf bank_mask:0xf
	v_mov_b32_dpp v241, v37 row_ror:8 row_mask:0xf bank_mask:0xf
	v_mov_b32_dpp v242, v38 row_ror:8 row_mask:0xf bank_mask:0xf
	v_mov_b32_dpp v243, v39 row_ror:8 row_mask:0xf bank_mask:0xf
	s_nop 0
	v_cndmask_b32_e64 v236, v236, v36, s[98:99]
	v_cndmask_b32_e64 v237, v237, v37, s[98:99]
	v_cndmask_b32_e64 v238, v238, v38, s[98:99]
	v_cndmask_b32_e64 v239, v239, v39, s[98:99]
	v_cndmask_b32_e64 v240, v32, v240, s[98:99]
	v_cndmask_b32_e64 v241, v33, v241, s[98:99]
	v_cndmask_b32_e64 v242, v34, v242, s[98:99]
	v_cndmask_b32_e64 v243, v35, v243, s[98:99]
	global_store_dwordx4 v[228:229], v[236:239], off offset:512 nt
	global_store_dwordx4 v[232:233], v[240:243], off offset:512 nt
	v_addc_co_u32_e32 v43, vcc, 0, v145, vcc
	v_lshl_add_u64 v[40:41], v[144:145], 0, s[14:15]
	global_load_dwordx4 v[32:35], v[42:43], off
	global_load_dwordx4 v[36:39], v[40:41], off offset:16
	s_waitcnt vmcnt(1)
	v_pk_add_f32 v[30:31], v[30:31], v[34:35]
	v_pk_add_f32 v[28:29], v[28:29], v[32:33]
	s_waitcnt vmcnt(0)
	v_pk_add_f32 v[26:27], v[26:27], v[38:39]
	v_pk_add_f32 v[24:25], v[24:25], v[36:37]
	v_lshl_add_u64 v[228:229], v[42:43], 0, v[230:231]
	v_lshl_add_u64 v[232:233], v[40:41], 0, v[244:245]
	s_nop 1
	v_mov_b32_dpp v236, v24 row_ror:8 row_mask:0xf bank_mask:0xf
	v_mov_b32_dpp v237, v25 row_ror:8 row_mask:0xf bank_mask:0xf
	v_mov_b32_dpp v238, v26 row_ror:8 row_mask:0xf bank_mask:0xf
	v_mov_b32_dpp v239, v27 row_ror:8 row_mask:0xf bank_mask:0xf
	v_mov_b32_dpp v240, v28 row_ror:8 row_mask:0xf bank_mask:0xf
	v_mov_b32_dpp v241, v29 row_ror:8 row_mask:0xf bank_mask:0xf
	v_mov_b32_dpp v242, v30 row_ror:8 row_mask:0xf bank_mask:0xf
	v_mov_b32_dpp v243, v31 row_ror:8 row_mask:0xf bank_mask:0xf
	s_nop 0
	v_cndmask_b32_e64 v236, v236, v28, s[98:99]
	v_cndmask_b32_e64 v237, v237, v29, s[98:99]
	v_cndmask_b32_e64 v238, v238, v30, s[98:99]
	v_cndmask_b32_e64 v239, v239, v31, s[98:99]
	v_cndmask_b32_e64 v240, v24, v240, s[98:99]
	v_cndmask_b32_e64 v241, v25, v241, s[98:99]
	v_cndmask_b32_e64 v242, v26, v242, s[98:99]
	v_cndmask_b32_e64 v243, v27, v243, s[98:99]
	global_store_dwordx4 v[228:229], v[236:239], off nt
	global_store_dwordx4 v[232:233], v[240:243], off nt
	global_load_dwordx4 v[24:27], v[40:41], off offset:528
	s_nop 0
	global_load_dwordx4 v[28:31], v[40:41], off offset:512
	s_waitcnt vmcnt(1)
	v_pk_add_f32 v[18:19], v[18:19], v[26:27]
	s_waitcnt vmcnt(0)
;     __device__ __forceinline__ void operator()(const f32x4 (&acc)[2][2][4][2], const Unit& u, int wr, int wc, int fr, int fq, const PG8_LAS float*) const {
;     ...
;             for (int m = 0; m < 4; ++m) { const int row = row0 + ai * HALF + m * 16; const size_t off = (size_t)row * ldc + col0; float ss = 0.f;
; #pragma unroll
;                 for (int bj = 0; bj < 2; ++bj) {
;                     const f32x4 b0 = *(const f32x4*)(base + off + bj * HALF), b1 = *(const f32x4*)(base + off + bj * HALF + 4);
;                     const f32x4 v0 = b0 + acc[ai][bj][m][0], v1 = b1 + acc[ai][bj][m][1];
;                     *(f32x4*)(out + off + bj * HALF) = v0; *(f32x4*)(out + off + bj * HALF + 4) = v1;
; template <class Epi, class Sched, bool ALIGN_EPI = false, bool SP2 = false>
; __device__ __forceinline__ void gemm_phase(PG8_LAS unsigned char* lds, const Gemm g, const Sched& S, const Epi& E) {
;     ...
;         if (!has_next) break;
	v_pk_add_f32 v[22:23], v[22:23], v[30:31]
	v_pk_add_f32 v[20:21], v[20:21], v[28:29]
	v_add_co_u32_e32 v26, vcc, s53, v144
	v_pk_add_f32 v[16:17], v[16:17], v[24:25]
	v_lshl_add_u64 v[228:229], v[40:41], 0, v[230:231]
	v_lshl_add_u64 v[232:233], v[40:41], 0, v[244:245]
	s_nop 1
	v_mov_b32_dpp v236, v16 row_ror:8 row_mask:0xf bank_mask:0xf
	v_mov_b32_dpp v237, v17 row_ror:8 row_mask:0xf bank_mask:0xf
	v_mov_b32_dpp v238, v18 row_ror:8 row_mask:0xf bank_mask:0xf
	v_mov_b32_dpp v239, v19 row_ror:8 row_mask:0xf bank_mask:0xf
	v_mov_b32_dpp v240, v20 row_ror:8 row_mask:0xf bank_mask:0xf
	v_mov_b32_dpp v241, v21 row_ror:8 row_mask:0xf bank_mask:0xf
	v_mov_b32_dpp v242, v22 row_ror:8 row_mask:0xf bank_mask:0xf
	v_mov_b32_dpp v243, v23 row_ror:8 row_mask:0xf bank_mask:0xf
	s_nop 0
	v_cndmask_b32_e64 v236, v236, v20, s[98:99]
	v_cndmask_b32_e64 v237, v237, v21, s[98:99]
	v_cndmask_b32_e64 v238, v238, v22, s[98:99]
	v_cndmask_b32_e64 v239, v239, v23, s[98:99]
	v_cndmask_b32_e64 v240, v16, v240, s[98:99]
	v_cndmask_b32_e64 v241, v17, v241, s[98:99]
	v_cndmask_b32_e64 v242, v18, v242, s[98:99]
	v_cndmask_b32_e64 v243, v19, v243, s[98:99]
	global_store_dwordx4 v[228:229], v[236:239], off offset:512 nt
	global_store_dwordx4 v[232:233], v[240:243], off offset:512 nt
	v_addc_co_u32_e32 v27, vcc, 0, v145, vcc
	s_nop 0
	v_lshl_add_u64 v[16:17], v[144:145], 0, s[16:17]
	global_load_dwordx4 v[18:21], v[26:27], off
	global_load_dwordx4 v[22:25], v[16:17], off offset:16
	s_andn2_b64 vcc, exec, s[2:3]
	s_waitcnt vmcnt(1)
	v_pk_add_f32 v[14:15], v[14:15], v[20:21]
	v_pk_add_f32 v[12:13], v[12:13], v[18:19]
	s_waitcnt vmcnt(0)
	v_pk_add_f32 v[10:11], v[10:11], v[24:25]
	v_pk_add_f32 v[8:9], v[8:9], v[22:23]
	v_lshl_add_u64 v[228:229], v[26:27], 0, v[230:231]
	v_lshl_add_u64 v[232:233], v[16:17], 0, v[244:245]
	s_nop 1
	v_mov_b32_dpp v236, v8 row_ror:8 row_mask:0xf bank_mask:0xf
	v_mov_b32_dpp v237, v9 row_ror:8 row_mask:0xf bank_mask:0xf
	v_mov_b32_dpp v238, v10 row_ror:8 row_mask:0xf bank_mask:0xf
	v_mov_b32_dpp v239, v11 row_ror:8 row_mask:0xf bank_mask:0xf
	v_mov_b32_dpp v240, v12 row_ror:8 row_mask:0xf bank_mask:0xf
	v_mov_b32_dpp v241, v13 row_ror:8 row_mask:0xf bank_mask:0xf
	v_mov_b32_dpp v242, v14 row_ror:8 row_mask:0xf bank_mask:0xf
	v_mov_b32_dpp v243, v15 row_ror:8 row_mask:0xf bank_mask:0xf
	s_nop 0
	v_cndmask_b32_e64 v236, v236, v12, s[98:99]
	v_cndmask_b32_e64 v237, v237, v13, s[98:99]
	v_cndmask_b32_e64 v238, v238, v14, s[98:99]
	v_cndmask_b32_e64 v239, v239, v15, s[98:99]
	v_cndmask_b32_e64 v240, v8, v240, s[98:99]
	v_cndmask_b32_e64 v241, v9, v241, s[98:99]
	v_cndmask_b32_e64 v242, v10, v242, s[98:99]
	v_cndmask_b32_e64 v243, v11, v243, s[98:99]
	global_store_dwordx4 v[228:229], v[236:239], off nt
	global_store_dwordx4 v[232:233], v[240:243], off nt
	global_load_dwordx4 v[8:11], v[16:17], off offset:528
	s_nop 0
	global_load_dwordx4 v[12:15], v[16:17], off offset:512
	s_waitcnt vmcnt(1)
	v_pk_add_f32 v[2:3], v[2:3], v[10:11]
	s_waitcnt vmcnt(0)
	v_pk_add_f32 v[6:7], v[6:7], v[14:15]
	v_pk_add_f32 v[4:5], v[4:5], v[12:13]
	v_pk_add_f32 v[0:1], v[0:1], v[8:9]
	v_lshl_add_u64 v[228:229], v[16:17], 0, v[230:231]
	v_lshl_add_u64 v[232:233], v[16:17], 0, v[244:245]
	s_nop 1
	v_mov_b32_dpp v236, v0 row_ror:8 row_mask:0xf bank_mask:0xf
	v_mov_b32_dpp v237, v1 row_ror:8 row_mask:0xf bank_mask:0xf
	v_mov_b32_dpp v238, v2 row_ror:8 row_mask:0xf bank_mask:0xf
	v_mov_b32_dpp v239, v3 row_ror:8 row_mask:0xf bank_mask:0xf
	v_mov_b32_dpp v240, v4 row_ror:8 row_mask:0xf bank_mask:0xf
	v_mov_b32_dpp v241, v5 row_ror:8 row_mask:0xf bank_mask:0xf
	v_mov_b32_dpp v242, v6 row_ror:8 row_mask:0xf bank_mask:0xf
	v_mov_b32_dpp v243, v7 row_ror:8 row_mask:0xf bank_mask:0xf
	s_nop 0
	v_cndmask_b32_e64 v236, v236, v4, s[98:99]
	v_cndmask_b32_e64 v237, v237, v5, s[98:99]
	v_cndmask_b32_e64 v238, v238, v6, s[98:99]
	v_cndmask_b32_e64 v239, v239, v7, s[98:99]
	v_cndmask_b32_e64 v240, v0, v240, s[98:99]
	v_cndmask_b32_e64 v241, v1, v241, s[98:99]
	v_cndmask_b32_e64 v242, v2, v242, s[98:99]
	v_cndmask_b32_e64 v243, v3, v243, s[98:99]
	global_store_dwordx4 v[228:229], v[236:239], off offset:512 nt
	global_store_dwordx4 v[232:233], v[240:243], off offset:512 nt
	s_cbranch_vccnz .LBB0_1633
	s_andn2_b64 vcc, exec, s[4:5]
	s_cbranch_vccnz .LBB0_1632
	s_barrier
	s_branch .LBB0_1632
